# pool mixer: the three row loads of each window step issued together (one memory round trip per step instead of three)
# baseline (speedup 1.0000x reference)
; __device__ __forceinline__ unsigned cvt_pk_bf16(float lo, float hi) { unsigned r; asm("v_cvt_pk_bf16_f32 %0, %1, %2" : "=v"(r) : "v"(lo), "v"(hi)); return r; }
; __device__ __forceinline__ float h_lo(unsigned w) { if (X_BF16) return bf_lo(w); return (float)__builtin_bit_cast(_Float16, (unsigned short)(w & 0xffffu)); }
; __device__ __forceinline__ float h_hi(unsigned w) { if (X_BF16) return bf_hi(w); return (float)__builtin_bit_cast(_Float16, (unsigned short)(w >> 16)); }
; __device__ __forceinline__ void poolmix_phase(const bf16_t* __restrict__ XB, const pg8::ssq_t* __restrict__ ssq, const float* __restrict__ g, bf16_t* __restrict__ MX, int row_lo, int nrows, int gtid, int nthr, LAS unsigned char* lds, int tid) {
;     ...
;         for (int k = 0; k < 16; ++k) {
;             const int t = t0 + k;
;             const int lo = max(t - hw, 0), hi = min(t + w - hw, SEQ);
;             const float inv = 1.f / (float)(hi - lo), rs = sb[t];
;             const u32x4 sv = *(const u32x4*)(base + (size_t)t * D);
;             u32x4 o;
;             o.x = cvt_pk_bf16((a[0] * inv - pg8::h_lo(sv.x) * rs) * g0[0], (a[1] * inv - pg8::h_hi(sv.x) * rs) * g0[1]);
;             o.y = cvt_pk_bf16((a[2] * inv - pg8::h_lo(sv.y) * rs) * g0[2], (a[3] * inv - pg8::h_hi(sv.y) * rs) * g0[3]);
;             o.z = cvt_pk_bf16((a[4] * inv - pg8::h_lo(sv.z) * rs) * g1[0], (a[5] * inv - pg8::h_hi(sv.z) * rs) * g1[1]);
;             o.w = cvt_pk_bf16((a[6] * inv - pg8::h_lo(sv.w) * rs) * g1[2], (a[7] * inv - pg8::h_hi(sv.w) * rs) * g1[3]);
;             *(u32x4*)(MX + (size_t)(tg0 + k) * D + ch) = o;
;             PM_V(t + w - hw, 1.f); PM_V(t - hw, -1.f);
;         }
.LBB0_166:
	v_add_u32_e32 v35, v30, v31
	v_max_i32_e32 v8, 0, v31
	v_min_i32_e32 v9, 0x800, v35
	v_sub_u32_e32 v8, v9, v8
	v_cvt_f32_i32_e32 v8, v8
	ds_read_b32 v39, v33 offset:32
	v_mov_b32_e32 v38, v16
	v_div_scale_f32 v9, s[14:15], v8, v8, 1.0
	v_rcp_f32_e32 v10, v9
	s_nop 0
	v_fma_f32 v11, -v9, v10, 1.0
	v_fmac_f32_e32 v10, v11, v10
	v_div_scale_f32 v11, vcc, 1.0, v8, 1.0
	v_mul_f32_e32 v36, v11, v10
	v_fma_f32 v37, -v9, v36, v11
	v_fmac_f32_e32 v36, v37, v10
	v_fma_f32 v9, -v9, v36, v11
	v_div_fmas_f32 v9, v9, v10, v36
	v_div_fixup_f32 v36, v9, v8, 1.0
	v_lshl_add_u64 v[8:9], v[26:27], 0, s[12:13]
	global_load_dwordx4 v[8:11], v[8:9], off
	v_cmp_gt_u32_e32 vcc, s57, v35
	s_and_saveexec_b64 s[14:15], vcc
	v_add_u32_e32 v176, s12, v28
	v_lshl_add_u64 v[44:45], v[12:13], 0, v[176:177]
	global_load_dwordx4 v[44:47], v[44:45], off
	s_or_b64 exec, exec, s[14:15]
	v_cmp_gt_u32_e32 vcc, s57, v31
	s_and_saveexec_b64 s[14:15], vcc
	v_add_u32_e32 v176, s12, v14
	v_lshl_add_u64 v[48:49], v[12:13], 0, v[176:177]
	global_load_dwordx4 v[48:51], v[48:49], off
	s_or_b64 exec, exec, s[14:15]
	s_waitcnt vmcnt(2)
	v_lshlrev_b32_e32 v37, 16, v8
	s_waitcnt lgkmcnt(0)
	v_pk_mul_f32 v[40:41], v[38:39], v[36:37]
	v_mov_b32_e32 v38, v17
	v_sub_f32_e32 v37, v40, v41
	v_mul_f32_e32 v42, v4, v37
	v_and_b32_e32 v37, 0xffff0000, v8
	v_pk_mul_f32 v[40:41], v[38:39], v[36:37]
	v_lshlrev_b32_e32 v37, 16, v9
	v_mov_b32_e32 v38, v18
	v_sub_f32_e32 v8, v40, v41
	v_pk_mul_f32 v[40:41], v[38:39], v[36:37]
	v_mul_f32_e32 v8, v5, v8
	v_sub_f32_e32 v37, v40, v41
	v_cvt_pk_bf16_f32 v8, v42, v8
	v_mul_f32_e32 v42, v6, v37
	v_and_b32_e32 v37, 0xffff0000, v9
	v_mov_b32_e32 v38, v19
	v_pk_mul_f32 v[40:41], v[38:39], v[36:37]
	v_lshlrev_b32_e32 v37, 16, v10
	v_mov_b32_e32 v38, v20
	v_sub_f32_e32 v9, v40, v41
	v_pk_mul_f32 v[40:41], v[38:39], v[36:37]
	v_mul_f32_e32 v9, v7, v9
	v_sub_f32_e32 v37, v40, v41
	v_cvt_pk_bf16_f32 v9, v42, v9
	v_mul_f32_e32 v42, v0, v37
	v_and_b32_e32 v37, 0xffff0000, v10
	v_mov_b32_e32 v38, v21
	v_pk_mul_f32 v[40:41], v[38:39], v[36:37]
	v_lshlrev_b32_e32 v37, 16, v11
	v_mov_b32_e32 v38, v22
	v_sub_f32_e32 v10, v40, v41
	v_pk_mul_f32 v[40:41], v[38:39], v[36:37]
	v_mov_b32_e32 v38, v23
	v_sub_f32_e32 v37, v40, v41
	v_mul_f32_e32 v40, v2, v37
	v_and_b32_e32 v37, 0xffff0000, v11
	v_pk_mul_f32 v[36:37], v[38:39], v[36:37]
	v_mul_f32_e32 v10, v1, v10
	v_sub_f32_e32 v11, v36, v37
	v_mul_f32_e32 v11, v3, v11
	v_lshl_add_u64 v[36:37], v[24:25], 0, s[12:13]
	v_cvt_pk_bf16_f32 v10, v42, v10
	v_cvt_pk_bf16_f32 v11, v40, v11
	global_store_dwordx4 v[36:37], v[8:11], off
	v_cmp_gt_u32_e32 vcc, s57, v35
	s_and_saveexec_b64 s[14:15], vcc
	s_cbranch_execz .LBB0_168
	v_add_u32_e32 v35, v33, v32
	ds_read_b32 v36, v35
	s_waitcnt vmcnt(2)
	v_lshlrev_b32_e32 v38, 16, v44
	v_and_b32_e32 v39, 0xffff0000, v44
	v_lshlrev_b32_e32 v8, 16, v45
	v_and_b32_e32 v9, 0xffff0000, v45
	s_waitcnt lgkmcnt(0)
	v_pk_fma_f32 v[18:19], v[36:37], v[8:9], v[18:19] op_sel_hi:[0,1,1]
	v_lshlrev_b32_e32 v8, 16, v46
	v_and_b32_e32 v9, 0xffff0000, v46
	v_pk_fma_f32 v[20:21], v[36:37], v[8:9], v[20:21] op_sel_hi:[0,1,1]
	v_lshlrev_b32_e32 v8, 16, v47
	v_and_b32_e32 v9, 0xffff0000, v47
	v_pk_fma_f32 v[16:17], v[36:37], v[38:39], v[16:17] op_sel_hi:[0,1,1]
	v_pk_fma_f32 v[22:23], v[36:37], v[8:9], v[22:23] op_sel_hi:[0,1,1]
.LBB0_168:
	s_or_b64 exec, exec, s[14:15]
	v_cmp_gt_u32_e32 vcc, s57, v31
	s_and_saveexec_b64 s[14:15], vcc
	s_cbranch_execz .LBB0_165
	v_add_u32_e32 v35, v33, v34
	ds_read_b32 v36, v35
	s_waitcnt vmcnt(1)
	v_lshlrev_b32_e32 v38, 16, v48
	v_and_b32_e32 v39, 0xffff0000, v48
	v_lshlrev_b32_e32 v8, 16, v49
	v_and_b32_e32 v9, 0xffff0000, v49
	s_waitcnt lgkmcnt(0)
	v_pk_fma_f32 v[18:19], v[36:37], v[8:9], v[18:19] op_sel_hi:[0,1,1] neg_lo:[1,0,0] neg_hi:[1,0,0]
	v_lshlrev_b32_e32 v8, 16, v50
	v_and_b32_e32 v9, 0xffff0000, v50
	v_pk_fma_f32 v[20:21], v[36:37], v[8:9], v[20:21] op_sel_hi:[0,1,1] neg_lo:[1,0,0] neg_hi:[1,0,0]
	v_lshlrev_b32_e32 v8, 16, v51
	v_and_b32_e32 v9, 0xffff0000, v51
	v_pk_fma_f32 v[16:17], v[36:37], v[38:39], v[16:17] op_sel_hi:[0,1,1] neg_lo:[1,0,0] neg_hi:[1,0,0]
	v_pk_fma_f32 v[22:23], v[36:37], v[8:9], v[22:23] op_sel_hi:[0,1,1] neg_lo:[1,0,0] neg_hi:[1,0,0]
	s_branch .LBB0_165
